# arrival ticket: generation and leader test from the barrier number instead of the division emulation (21 fewer instructions on the arrival path), on top of the census removal
# baseline (speedup 1.0000x reference)
; DI unsigned xb_add(unsigned* p, unsigned v) { return __hip_atomic_fetch_add(p, v, __ATOMIC_RELAXED, __HIP_MEMORY_SCOPE_AGENT); }
; DI void xcd_barrier(unsigned* bar, volatile __attribute__((address_space(3))) unsigned* st) {
;     ...
;         const unsigned old = xb_add(&bar[XB_XSUB(x)], 1u);
;         const unsigned gen = old / nloc;
;         if (old + 1u == (gen + 1u) * nloc) {
.LBB0_150:
	s_or_b64 exec, exec, s[8:9]
	s_waitcnt vmcnt(0)
	v_readfirstlane_b32 s3, v3
	v_mul_u32_u24_e32 v2, 1, v2
	s_nop 0
	v_add_u32_e32 v5, s3, v0
	v_mov_b32_e32 v0, 0
	v_add_u32_e32 v3, 1, v5
	v_cmp_ne_u32_e32 vcc, v3, v2
	s_and_saveexec_b64 s[6:7], vcc
	s_xor_b64 s[6:7], exec, s[6:7]
	s_cbranch_execz .LBB0_164
	buffer_inv sc1
	s_waitcnt lgkmcnt(0)
	v_mul_u32_u24_e32 v4, 1, v1
	v_mov_b32_e32 v2, 0x34e5000

; DI unsigned xb_add(unsigned* p, unsigned v) { return __hip_atomic_fetch_add(p, v, __ATOMIC_RELAXED, __HIP_MEMORY_SCOPE_AGENT); }
; DI void xcd_barrier(unsigned* bar, volatile __attribute__((address_space(3))) unsigned* st) {
;     ...
;         const unsigned old = xb_add(&bar[XB_XSUB(x)], 1u);
;         const unsigned gen = old / nloc;
;         if (old + 1u == (gen + 1u) * nloc) {
.LBB0_240:
	s_or_b64 exec, exec, s[10:11]
	s_waitcnt vmcnt(0)
	v_readfirstlane_b32 s3, v3
	v_mul_u32_u24_e32 v2, 2, v2
	s_nop 0
	v_add_u32_e32 v5, s3, v0
	v_mov_b32_e32 v0, 1
	v_add_u32_e32 v3, 1, v5
	v_cmp_ne_u32_e32 vcc, v3, v2
	s_and_saveexec_b64 s[8:9], vcc
	s_xor_b64 s[8:9], exec, s[8:9]
	s_cbranch_execz .LBB0_254
	buffer_inv sc1
	s_waitcnt lgkmcnt(0)
	v_mul_u32_u24_e32 v4, 2, v1
	v_mov_b32_e32 v2, 0x34e5000

; DI unsigned xb_add(unsigned* p, unsigned v) { return __hip_atomic_fetch_add(p, v, __ATOMIC_RELAXED, __HIP_MEMORY_SCOPE_AGENT); }
; DI void xcd_barrier(unsigned* bar, volatile __attribute__((address_space(3))) unsigned* st) {
;     ...
;         const unsigned old = xb_add(&bar[XB_XSUB(x)], 1u);
;         const unsigned gen = old / nloc;
;         if (old + 1u == (gen + 1u) * nloc) {
.LBB0_323:
	s_or_b64 exec, exec, s[10:11]
	s_waitcnt vmcnt(0)
	v_readfirstlane_b32 s3, v3
	v_mul_u32_u24_e32 v2, 3, v2
	s_nop 0
	v_add_u32_e32 v5, s3, v0
	v_mov_b32_e32 v0, 2
	v_add_u32_e32 v3, 1, v5
	v_cmp_ne_u32_e32 vcc, v3, v2
	s_and_saveexec_b64 s[8:9], vcc
	s_xor_b64 s[8:9], exec, s[8:9]
	s_cbranch_execz .LBB0_337
	buffer_inv sc1
	s_waitcnt lgkmcnt(0)
	v_mul_u32_u24_e32 v4, 3, v1
	v_mov_b32_e32 v2, 0x34e5000

; DI unsigned xb_add(unsigned* p, unsigned v) { return __hip_atomic_fetch_add(p, v, __ATOMIC_RELAXED, __HIP_MEMORY_SCOPE_AGENT); }
; DI void xcd_barrier(unsigned* bar, volatile __attribute__((address_space(3))) unsigned* st) {
;     ...
;         const unsigned old = xb_add(&bar[XB_XSUB(x)], 1u);
;         const unsigned gen = old / nloc;
;         if (old + 1u == (gen + 1u) * nloc) {
.LBB0_400:
	s_or_b64 exec, exec, s[8:9]
	s_waitcnt vmcnt(0)
	v_readfirstlane_b32 s3, v3
	v_mul_u32_u24_e32 v2, 4, v2
	s_nop 0
	v_add_u32_e32 v5, s3, v0
	v_mov_b32_e32 v0, 3
	v_add_u32_e32 v3, 1, v5
	v_cmp_ne_u32_e32 vcc, v3, v2
	s_and_saveexec_b64 s[6:7], vcc
	s_xor_b64 s[6:7], exec, s[6:7]
	s_cbranch_execz .LBB0_414
	buffer_inv sc1
	s_waitcnt lgkmcnt(0)
	v_mul_u32_u24_e32 v4, 4, v1
	v_mov_b32_e32 v2, 0x34e5000

; DI unsigned xb_add(unsigned* p, unsigned v) { return __hip_atomic_fetch_add(p, v, __ATOMIC_RELAXED, __HIP_MEMORY_SCOPE_AGENT); }
; DI void xcd_barrier(unsigned* bar, volatile __attribute__((address_space(3))) unsigned* st) {
;     ...
;         const unsigned old = xb_add(&bar[XB_XSUB(x)], 1u);
;         const unsigned gen = old / nloc;
;         if (old + 1u == (gen + 1u) * nloc) {
.LBB0_490:
	s_or_b64 exec, exec, s[10:11]
	s_waitcnt vmcnt(0)
	v_readfirstlane_b32 s3, v3
	v_mul_u32_u24_e32 v2, 5, v2
	s_nop 0
	v_add_u32_e32 v5, s3, v0
	v_mov_b32_e32 v0, 4
	v_add_u32_e32 v3, 1, v5
	v_cmp_ne_u32_e32 vcc, v3, v2
	s_and_saveexec_b64 s[8:9], vcc
	s_xor_b64 s[8:9], exec, s[8:9]
	s_cbranch_execz .LBB0_504
	buffer_inv sc1
	s_waitcnt lgkmcnt(0)
	v_mul_u32_u24_e32 v4, 5, v1
	v_mov_b32_e32 v2, 0x34e5000

; DI unsigned xb_add(unsigned* p, unsigned v) { return __hip_atomic_fetch_add(p, v, __ATOMIC_RELAXED, __HIP_MEMORY_SCOPE_AGENT); }
; DI void xcd_barrier(unsigned* bar, volatile __attribute__((address_space(3))) unsigned* st) {
;     ...
;         const unsigned old = xb_add(&bar[XB_XSUB(x)], 1u);
;         const unsigned gen = old / nloc;
;         if (old + 1u == (gen + 1u) * nloc) {
.LBB0_598:
	s_or_b64 exec, exec, s[8:9]
	s_waitcnt vmcnt(0)
	v_readfirstlane_b32 s3, v3
	v_mul_u32_u24_e32 v2, 6, v2
	s_nop 0
	v_add_u32_e32 v5, s3, v0
	v_mov_b32_e32 v0, 5
	v_add_u32_e32 v3, 1, v5
	v_cmp_ne_u32_e32 vcc, v3, v2
	s_and_saveexec_b64 s[6:7], vcc
	s_xor_b64 s[6:7], exec, s[6:7]
	s_cbranch_execz .LBB0_612
	buffer_inv sc1
	s_waitcnt lgkmcnt(0)
	v_mul_u32_u24_e32 v4, 6, v1
	v_mov_b32_e32 v2, 0x34e5000

; DI unsigned xb_add(unsigned* p, unsigned v) { return __hip_atomic_fetch_add(p, v, __ATOMIC_RELAXED, __HIP_MEMORY_SCOPE_AGENT); }
; DI void xcd_barrier(unsigned* bar, volatile __attribute__((address_space(3))) unsigned* st) {
;     ...
;         const unsigned old = xb_add(&bar[XB_XSUB(x)], 1u);
;         const unsigned gen = old / nloc;
;         if (old + 1u == (gen + 1u) * nloc) {
.LBB0_680:
	s_or_b64 exec, exec, s[8:9]
	s_waitcnt vmcnt(0)
	v_readfirstlane_b32 s3, v3
	v_mul_u32_u24_e32 v2, 7, v2
	s_nop 0
	v_add_u32_e32 v5, s3, v0
	v_mov_b32_e32 v0, 6
	v_add_u32_e32 v3, 1, v5
	v_cmp_ne_u32_e32 vcc, v3, v2
	s_and_saveexec_b64 s[6:7], vcc
	s_xor_b64 s[6:7], exec, s[6:7]
	s_cbranch_execz .LBB0_694
	buffer_inv sc1
	s_waitcnt lgkmcnt(0)
	v_mul_u32_u24_e32 v4, 7, v1
	v_mov_b32_e32 v2, 0x34e5000

; DI unsigned xb_add(unsigned* p, unsigned v) { return __hip_atomic_fetch_add(p, v, __ATOMIC_RELAXED, __HIP_MEMORY_SCOPE_AGENT); }
; DI void xcd_barrier(unsigned* bar, volatile __attribute__((address_space(3))) unsigned* st) {
;     ...
;         const unsigned old = xb_add(&bar[XB_XSUB(x)], 1u);
;         const unsigned gen = old / nloc;
;         if (old + 1u == (gen + 1u) * nloc) {
.LBB0_801:
	s_or_b64 exec, exec, s[8:9]
	s_waitcnt vmcnt(0)
	v_readfirstlane_b32 s3, v3
	v_mul_u32_u24_e32 v2, 8, v2
	s_nop 0
	v_add_u32_e32 v5, s3, v0
	v_mov_b32_e32 v0, 7
	v_add_u32_e32 v3, 1, v5
	v_cmp_ne_u32_e32 vcc, v3, v2
	s_and_saveexec_b64 s[6:7], vcc
	s_xor_b64 s[6:7], exec, s[6:7]
	s_cbranch_execz .LBB0_815
	buffer_inv sc1
	s_waitcnt lgkmcnt(0)
	v_mul_u32_u24_e32 v4, 8, v1
	v_mov_b32_e32 v2, 0x34e5000

; DI unsigned xb_add(unsigned* p, unsigned v) { return __hip_atomic_fetch_add(p, v, __ATOMIC_RELAXED, __HIP_MEMORY_SCOPE_AGENT); }
; DI void xcd_barrier(unsigned* bar, volatile __attribute__((address_space(3))) unsigned* st) {
;     ...
;         const unsigned old = xb_add(&bar[XB_XSUB(x)], 1u);
;         const unsigned gen = old / nloc;
;         if (old + 1u == (gen + 1u) * nloc) {
.LBB0_877:
	s_or_b64 exec, exec, s[10:11]
	s_waitcnt vmcnt(0)
	v_readfirstlane_b32 s3, v3
	v_mul_u32_u24_e32 v2, 9, v2
	s_nop 0
	v_add_u32_e32 v5, s3, v0
	v_mov_b32_e32 v0, 8
	v_add_u32_e32 v3, 1, v5
	v_cmp_ne_u32_e32 vcc, v3, v2
	s_and_saveexec_b64 s[8:9], vcc
	s_xor_b64 s[8:9], exec, s[8:9]
	s_cbranch_execz .LBB0_891
	buffer_inv sc1
	s_waitcnt lgkmcnt(0)
	v_mul_u32_u24_e32 v4, 9, v1
	v_mov_b32_e32 v2, 0x34e5000

; DI int fresh_tid() { int t = threadIdx.x; asm volatile("" : "+v"(t)); return t; }
; DI void xcd_barrier(unsigned* bar, volatile __attribute__((address_space(3))) unsigned* st) {
;     asm volatile("s_waitcnt vmcnt(0)" ::: "memory");
;     __syncthreads();
;     if (fresh_tid() == 0) {
.LBB0_935:
	s_waitcnt vmcnt(0)
	v_mov_b32_e32 v0, v250
	s_barrier
	s_getpc_b64 vcc
	v_mov_b32_e32 v2, vcc_lo
	v_mov_b32_e32 v3, vcc_hi
	v_cmp_lt_u32_e32 vcc, 63, v0
	s_and_saveexec_b64 s[4:5], vcc
	s_cbranch_execz .Lcpf_s10
	v_lshlrev_b32_e32 v1, 6, v0
	v_subrev_u32_e32 v1, 0x1000, v1
	v_min_u32_e32 v1, 0x5a40, v1
	v_add_co_u32_e32 v2, vcc, v2, v1
	s_nop 1
	v_addc_co_u32_e32 v3, vcc, 0, v3, vcc
	global_load_dword v4, v[2:3], off

; DI unsigned xb_add(unsigned* p, unsigned v) { return __hip_atomic_fetch_add(p, v, __ATOMIC_RELAXED, __HIP_MEMORY_SCOPE_AGENT); }
; DI void xcd_barrier(unsigned* bar, volatile __attribute__((address_space(3))) unsigned* st) {
;     ...
;         const unsigned old = xb_add(&bar[XB_XSUB(x)], 1u);
;         const unsigned gen = old / nloc;
;         if (old + 1u == (gen + 1u) * nloc) {
.LBB0_953:
	s_or_b64 exec, exec, s[10:11]
	s_waitcnt vmcnt(0)
	v_readfirstlane_b32 s3, v3
	v_mul_u32_u24_e32 v2, 10, v2
	s_nop 0
	v_add_u32_e32 v5, s3, v0
	v_mov_b32_e32 v0, 9
	v_add_u32_e32 v3, 1, v5
	v_cmp_ne_u32_e32 vcc, v3, v2
	s_and_saveexec_b64 s[8:9], vcc
	s_xor_b64 s[8:9], exec, s[8:9]
	s_cbranch_execz .LBB0_967
	buffer_inv sc1
	s_waitcnt lgkmcnt(0)
	v_mul_u32_u24_e32 v4, 10, v1
	v_mov_b32_e32 v2, 0x34e5000

; DI int fresh_tid() { int t = threadIdx.x; asm volatile("" : "+v"(t)); return t; }
; DI void xcd_barrier(unsigned* bar, volatile __attribute__((address_space(3))) unsigned* st) {
;     asm volatile("s_waitcnt vmcnt(0)" ::: "memory");
;     __syncthreads();
;     if (fresh_tid() == 0) {
.LBB0_998:
	s_or_b64 exec, exec, s[6:7]
	s_waitcnt vmcnt(0)
	v_mov_b32_e32 v0, v250
	s_barrier
	s_getpc_b64 vcc
	v_mov_b32_e32 v2, vcc_lo
	v_mov_b32_e32 v3, vcc_hi
	v_cmp_lt_u32_e32 vcc, 63, v0
	s_and_saveexec_b64 s[4:5], vcc
	s_cbranch_execz .Lcpf_s11
	v_lshlrev_b32_e32 v1, 6, v0
	v_subrev_u32_e32 v1, 0x1000, v1
	v_min_u32_e32 v1, 0x4540, v1
	v_add_co_u32_e32 v2, vcc, v2, v1
	s_nop 1
	v_addc_co_u32_e32 v3, vcc, 0, v3, vcc
	global_load_dword v4, v[2:3], off

; DI unsigned xb_add(unsigned* p, unsigned v) { return __hip_atomic_fetch_add(p, v, __ATOMIC_RELAXED, __HIP_MEMORY_SCOPE_AGENT); }
; DI void xcd_barrier(unsigned* bar, volatile __attribute__((address_space(3))) unsigned* st) {
;     ...
;         const unsigned old = xb_add(&bar[XB_XSUB(x)], 1u);
;         const unsigned gen = old / nloc;
;         if (old + 1u == (gen + 1u) * nloc) {
.LBB0_1016:
	s_or_b64 exec, exec, s[12:13]
	s_waitcnt vmcnt(0)
	v_readfirstlane_b32 s3, v3
	v_mul_u32_u24_e32 v2, 11, v2
	s_nop 0
	v_add_u32_e32 v5, s3, v0
	v_mov_b32_e32 v0, 10
	v_add_u32_e32 v3, 1, v5
	v_cmp_ne_u32_e32 vcc, v3, v2
	s_and_saveexec_b64 s[8:9], vcc
	s_xor_b64 s[8:9], exec, s[8:9]
	s_cbranch_execz .LBB0_1030
	buffer_inv sc1
	s_waitcnt lgkmcnt(0)
	v_mul_u32_u24_e32 v4, 11, v1
	v_mov_b32_e32 v2, 0x34e5000

; DI int fresh_tid() { int t = threadIdx.x; asm volatile("" : "+v"(t)); return t; }
; DI void xcd_barrier(unsigned* bar, volatile __attribute__((address_space(3))) unsigned* st) {
;     asm volatile("s_waitcnt vmcnt(0)" ::: "memory");
;     __syncthreads();
;     if (fresh_tid() == 0) {
.LBB0_1092:
	s_waitcnt vmcnt(0)
	v_mov_b32_e32 v0, v250
	s_barrier
	s_getpc_b64 vcc
	v_mov_b32_e32 v2, vcc_lo
	v_mov_b32_e32 v3, vcc_hi
	v_cmp_lt_u32_e32 vcc, 63, v0
	s_and_saveexec_b64 s[4:5], vcc
	s_cbranch_execz .Lcpf_s12
	v_lshlrev_b32_e32 v1, 6, v0
	v_subrev_u32_e32 v1, 0x1000, v1
	v_min_u32_e32 v1, 0x25c0, v1
	v_add_co_u32_e32 v2, vcc, v2, v1
	s_nop 1
	v_addc_co_u32_e32 v3, vcc, 0, v3, vcc
	global_load_dword v4, v[2:3], off

; DI unsigned xb_add(unsigned* p, unsigned v) { return __hip_atomic_fetch_add(p, v, __ATOMIC_RELAXED, __HIP_MEMORY_SCOPE_AGENT); }
; DI void xcd_barrier(unsigned* bar, volatile __attribute__((address_space(3))) unsigned* st) {
;     ...
;         const unsigned old = xb_add(&bar[XB_XSUB(x)], 1u);
;         const unsigned gen = old / nloc;
;         if (old + 1u == (gen + 1u) * nloc) {
.LBB0_1110:
	s_or_b64 exec, exec, s[16:17]
	s_waitcnt vmcnt(0)
	v_readfirstlane_b32 s3, v3
	v_mul_u32_u24_e32 v2, 12, v2
	s_nop 0
	v_add_u32_e32 v5, s3, v0
	v_mov_b32_e32 v0, 11
	v_add_u32_e32 v3, 1, v5
	v_cmp_ne_u32_e32 vcc, v3, v2
	s_and_saveexec_b64 s[8:9], vcc
	s_xor_b64 s[8:9], exec, s[8:9]
	s_cbranch_execz .LBB0_1124
	buffer_inv sc1
	s_waitcnt lgkmcnt(0)
	v_mul_u32_u24_e32 v4, 12, v1
	v_mov_b32_e32 v2, 0x34e5000

; DI int fresh_tid() { int t = threadIdx.x; asm volatile("" : "+v"(t)); return t; }
; DI void xcd_barrier(unsigned* bar, volatile __attribute__((address_space(3))) unsigned* st) {
;     asm volatile("s_waitcnt vmcnt(0)" ::: "memory");
;     __syncthreads();
;     if (fresh_tid() == 0) {
.LBB0_1151:
	s_or_b64 exec, exec, s[6:7]
	s_waitcnt vmcnt(0)
	v_mov_b32_e32 v0, v250
	s_barrier
	s_getpc_b64 vcc
	v_mov_b32_e32 v2, vcc_lo
	v_mov_b32_e32 v3, vcc_hi
	v_cmp_lt_u32_e32 vcc, 63, v0
	s_and_saveexec_b64 s[4:5], vcc
	s_cbranch_execz .Lcpf_s13
	v_lshlrev_b32_e32 v1, 6, v0
	v_subrev_u32_e32 v1, 0x1000, v1
	v_min_u32_e32 v1, 0x2200, v1
	v_add_co_u32_e32 v2, vcc, v2, v1
	s_nop 1
	v_addc_co_u32_e32 v3, vcc, 0, v3, vcc
	global_load_dword v4, v[2:3], off

; DI unsigned xb_add(unsigned* p, unsigned v) { return __hip_atomic_fetch_add(p, v, __ATOMIC_RELAXED, __HIP_MEMORY_SCOPE_AGENT); }
; DI void xcd_barrier(unsigned* bar, volatile __attribute__((address_space(3))) unsigned* st) {
;     ...
;         const unsigned old = xb_add(&bar[XB_XSUB(x)], 1u);
;         const unsigned gen = old / nloc;
;         if (old + 1u == (gen + 1u) * nloc) {
.LBB0_1169:
	s_or_b64 exec, exec, s[12:13]
	s_waitcnt vmcnt(0)
	v_readfirstlane_b32 s3, v3
	v_mul_u32_u24_e32 v2, 13, v2
	s_nop 0
	v_add_u32_e32 v5, s3, v0
	v_mov_b32_e32 v0, 12
	v_add_u32_e32 v3, 1, v5
	v_cmp_ne_u32_e32 vcc, v3, v2
	s_and_saveexec_b64 s[8:9], vcc
	s_xor_b64 s[8:9], exec, s[8:9]
	s_cbranch_execz .LBB0_1183
	buffer_inv sc1
	s_waitcnt lgkmcnt(0)
	v_mul_u32_u24_e32 v4, 13, v1
	v_mov_b32_e32 v2, 0x34e5000

; DI int fresh_tid() { int t = threadIdx.x; asm volatile("" : "+v"(t)); return t; }
; DI void xcd_barrier(unsigned* bar, volatile __attribute__((address_space(3))) unsigned* st) {
;     asm volatile("s_waitcnt vmcnt(0)" ::: "memory");
;     __syncthreads();
;     if (fresh_tid() == 0) {
.LBB0_1231:
	s_waitcnt vmcnt(0)
	v_mov_b32_e32 v0, v250
	s_barrier
	s_getpc_b64 vcc
	v_mov_b32_e32 v2, vcc_lo
	v_mov_b32_e32 v3, vcc_hi
	v_cmp_lt_u32_e32 vcc, 63, v0
	s_and_saveexec_b64 s[0:1], vcc
	s_cbranch_execz .Lcpf_s14
	v_lshlrev_b32_e32 v1, 6, v0
	v_subrev_u32_e32 v1, 0x1000, v1
	v_min_u32_e32 v1, 0xa40, v1
	v_add_co_u32_e32 v2, vcc, v2, v1
	s_nop 1
	v_addc_co_u32_e32 v3, vcc, 0, v3, vcc
	global_load_dword v4, v[2:3], off

; DI unsigned xb_add(unsigned* p, unsigned v) { return __hip_atomic_fetch_add(p, v, __ATOMIC_RELAXED, __HIP_MEMORY_SCOPE_AGENT); }
; DI void xcd_barrier(unsigned* bar, volatile __attribute__((address_space(3))) unsigned* st) {
;     ...
;         const unsigned old = xb_add(&bar[XB_XSUB(x)], 1u);
;         const unsigned gen = old / nloc;
;         if (old + 1u == (gen + 1u) * nloc) {
.LBB0_1249:
	s_or_b64 exec, exec, s[6:7]
	s_waitcnt vmcnt(0)
	v_readfirstlane_b32 s4, v3
	v_mul_u32_u24_e32 v2, 14, v2
	s_nop 0
	v_add_u32_e32 v5, s4, v0
	v_mov_b32_e32 v0, 13
	v_add_u32_e32 v3, 1, v5
	v_cmp_ne_u32_e32 vcc, v3, v2
	s_and_saveexec_b64 s[4:5], vcc
	s_xor_b64 s[4:5], exec, s[4:5]
	s_cbranch_execz .LBB0_1263
	buffer_inv sc1
	s_waitcnt lgkmcnt(0)
	v_mul_u32_u24_e32 v4, 14, v1
	v_mov_b32_e32 v2, 0x34e5000
